# XCD barrier: non-leader workgroups poll TOPGEN directly instead of their XCD's XGEN (same generation numbering), removing the leader's poll+acquire+XGEN atomic from the release path of all 13 seams
# baseline (speedup 1.0000x reference)
; __device__ __forceinline__ unsigned xb_ld(unsigned* p)              { return __hip_atomic_load(p, __ATOMIC_RELAXED, __HIP_MEMORY_SCOPE_AGENT); }
; __device__ __forceinline__ unsigned xb_add(unsigned* p, unsigned v) { return __hip_atomic_fetch_add(p, v, __ATOMIC_RELAXED, __HIP_MEMORY_SCOPE_AGENT); }
; #define XB_SPIN(cond, bar) do { unsigned _sp = 0; while (cond) { __builtin_amdgcn_s_sleep(1); \
;     if ((++_sp & 255u) == 0u) { if (xb_ld(&(bar)[XB_TMO])) break; if (_sp > XB_SPIN_CAP) { atomicAdd(&(bar)[XB_TMO], 1u); break; } } } } while (0)
; __device__ __forceinline__ void xcd_barrier(const XcdBarrier& b) {
;     ...
;         unsigned nloc = b.st[0], nx = b.st[1];
;         if (nloc == 0u) { xcd_barrier_complete(bar, b.x, nloc, nx); b.st[0] = nloc; b.st[1] = nx; }
;         const unsigned old = xb_add(&bar[XB_XSUB(b.x)], 1u);
;         const unsigned gen = old / nloc;
;         if (old + 1u == (gen + 1u) * nloc) {
;             __builtin_amdgcn_fence(__ATOMIC_RELEASE, "agent");
;             asm volatile("s_waitcnt vmcnt(0)" ::: "memory");
;             const unsigned og = xb_add(&bar[XB_TOP], 1u);
;             const unsigned tg = og / nx;
;             if (og + 1u == (tg + 1u) * nx) xb_add(&bar[XB_TOPGEN], 1u);
;             else XB_SPIN(xb_ld(&bar[XB_TOPGEN]) == tg, bar);
;             __builtin_amdgcn_fence(__ATOMIC_ACQUIRE, "agent");
;             xb_add(&bar[XB_XGEN(b.x)], 1u);
;             asm volatile("s_waitcnt vmcnt(0)" ::: "memory");
;         } else {
;             XB_SPIN(xb_ld(&bar[XB_XGEN(b.x)]) == gen, bar);
.Lxs0_105:
	s_or_b64 exec, exec, s[6:7]
	v_cvt_f32_u32_e32 v4, v2
	s_waitcnt vmcnt(0)
	v_readfirstlane_b32 s4, v3
	v_sub_u32_e32 v3, 0, v2
	v_rcp_iflag_f32_e32 v4, v4
	v_add_u32_e32 v5, s4, v0
	v_mul_f32_e32 v4, 0x4f7ffffe, v4
	v_cvt_u32_f32_e32 v4, v4
	v_mul_lo_u32 v0, v3, v4
	v_mul_hi_u32 v0, v4, v0
	v_add_u32_e32 v0, v4, v0
	v_mul_hi_u32 v0, v5, v0
	v_mul_lo_u32 v3, v0, v2
	v_sub_u32_e32 v3, v5, v3
	v_add_u32_e32 v4, 1, v0
	v_cmp_ge_u32_e32 vcc, v3, v2
	s_nop 1
	v_cndmask_b32_e32 v0, v0, v4, vcc
	v_sub_u32_e32 v4, v3, v2
	v_cndmask_b32_e32 v3, v3, v4, vcc
	v_add_u32_e32 v4, 1, v0
	v_cmp_ge_u32_e32 vcc, v3, v2
	v_add_u32_e32 v3, 1, v5
	s_nop 0
	v_cndmask_b32_e32 v0, v0, v4, vcc
	v_mul_lo_u32 v4, v2, v0
	v_add_u32_e32 v2, v4, v2
	v_cmp_ne_u32_e32 vcc, v3, v2
	s_and_saveexec_b64 s[4:5], vcc
	s_xor_b64 s[4:5], exec, s[4:5]
	s_cbranch_execz .Lxs0_119
	s_waitcnt lgkmcnt(0)
	v_readlane_b32 s10, v228, 15
	v_readlane_b32 s11, v228, 16
	v_mov_b32_e32 v1, 0
	s_nop 4
	s_add_u32 s10, s10, 0x3500
	s_addc_u32 s11, s11, 0
	global_load_dword v1, v1, s[10:11] sc1


; __device__ __forceinline__ unsigned xb_ld(unsigned* p)              { return __hip_atomic_load(p, __ATOMIC_RELAXED, __HIP_MEMORY_SCOPE_AGENT); }
; #define XB_SPIN(cond, bar) do { unsigned _sp = 0; while (cond) { __builtin_amdgcn_s_sleep(1); \
;     if ((++_sp & 255u) == 0u) { if (xb_ld(&(bar)[XB_TMO])) break; if (_sp > XB_SPIN_CAP) { atomicAdd(&(bar)[XB_TMO], 1u); break; } } } } while (0)
; __device__ __forceinline__ void xcd_barrier(const XcdBarrier& b) {
;     ...
;             XB_SPIN(xb_ld(&bar[XB_XGEN(b.x)]) == gen, bar);
	s_waitcnt vmcnt(0)
	v_cmp_eq_u32_e32 vcc, v1, v0
	s_and_saveexec_b64 s[6:7], vcc
	s_cbranch_execz .Lxs0_118
	v_readlane_b32 s12, v228, 2
	v_readlane_b32 s18, v228, 8
	v_readlane_b32 s13, v228, 3
	v_readlane_b32 s19, v228, 9
	s_add_u32 s8, s18, 0x179ed200
	v_readlane_b32 s14, v228, 4
	v_readlane_b32 s15, v228, 5
	s_addc_u32 s9, s19, 0
	s_mov_b32 s22, 1
	s_mov_b64 s[12:13], 0
	v_mov_b32_e32 v1, 0
	v_readlane_b32 s16, v228, 6
	v_readlane_b32 s17, v228, 7
	s_branch .Lxs0_109

; __device__ __forceinline__ unsigned xb_ld(unsigned* p)              { return __hip_atomic_load(p, __ATOMIC_RELAXED, __HIP_MEMORY_SCOPE_AGENT); }
; __device__ __forceinline__ unsigned xb_add(unsigned* p, unsigned v) { return __hip_atomic_fetch_add(p, v, __ATOMIC_RELAXED, __HIP_MEMORY_SCOPE_AGENT); }
; #define XB_SPIN(cond, bar) do { unsigned _sp = 0; while (cond) { __builtin_amdgcn_s_sleep(1); \
;     if ((++_sp & 255u) == 0u) { if (xb_ld(&(bar)[XB_TMO])) break; if (_sp > XB_SPIN_CAP) { atomicAdd(&(bar)[XB_TMO], 1u); break; } } } } while (0)
; __device__ __forceinline__ void xcd_barrier(const XcdBarrier& b) {
;     ...
;         unsigned nloc = b.st[0], nx = b.st[1];
;         if (nloc == 0u) { xcd_barrier_complete(bar, b.x, nloc, nx); b.st[0] = nloc; b.st[1] = nx; }
;         const unsigned old = xb_add(&bar[XB_XSUB(b.x)], 1u);
;         const unsigned gen = old / nloc;
;         if (old + 1u == (gen + 1u) * nloc) {
;             __builtin_amdgcn_fence(__ATOMIC_RELEASE, "agent");
;             asm volatile("s_waitcnt vmcnt(0)" ::: "memory");
;             const unsigned og = xb_add(&bar[XB_TOP], 1u);
;             const unsigned tg = og / nx;
;             if (og + 1u == (tg + 1u) * nx) xb_add(&bar[XB_TOPGEN], 1u);
;             else XB_SPIN(xb_ld(&bar[XB_TOPGEN]) == tg, bar);
;             __builtin_amdgcn_fence(__ATOMIC_ACQUIRE, "agent");
;             xb_add(&bar[XB_XGEN(b.x)], 1u);
;             asm volatile("s_waitcnt vmcnt(0)" ::: "memory");
;         } else {
;             XB_SPIN(xb_ld(&bar[XB_XGEN(b.x)]) == gen, bar);
.LBB0_942:
	s_or_b64 exec, exec, s[6:7]
	v_cvt_f32_u32_e32 v4, v2
	s_waitcnt vmcnt(0)
	v_readfirstlane_b32 s4, v3
	v_sub_u32_e32 v3, 0, v2
	v_rcp_iflag_f32_e32 v4, v4
	v_add_u32_e32 v5, s4, v1
	v_mul_f32_e32 v4, 0x4f7ffffe, v4
	v_cvt_u32_f32_e32 v4, v4
	v_mul_lo_u32 v1, v3, v4
	v_mul_hi_u32 v1, v4, v1
	v_add_u32_e32 v1, v4, v1
	v_mul_hi_u32 v1, v5, v1
	v_mul_lo_u32 v3, v1, v2
	v_sub_u32_e32 v3, v5, v3
	v_add_u32_e32 v4, 1, v1
	v_cmp_ge_u32_e32 vcc, v3, v2
	s_nop 1
	v_cndmask_b32_e32 v1, v1, v4, vcc
	v_sub_u32_e32 v4, v3, v2
	v_cndmask_b32_e32 v3, v3, v4, vcc
	v_add_u32_e32 v4, 1, v1
	v_cmp_ge_u32_e32 vcc, v3, v2
	v_add_u32_e32 v3, 1, v5
	s_nop 0
	v_cndmask_b32_e32 v1, v1, v4, vcc
	v_mul_lo_u32 v4, v2, v1
	v_add_u32_e32 v2, v4, v2
	v_cmp_ne_u32_e32 vcc, v3, v2
	s_and_saveexec_b64 s[4:5], vcc
	s_xor_b64 s[4:5], exec, s[4:5]
	s_cbranch_execz .LBB0_956
	s_waitcnt lgkmcnt(0)
	v_readlane_b32 s10, v228, 15
	v_readlane_b32 s11, v228, 16
	v_mov_b32_e32 v0, 0
	s_nop 4
	s_add_u32 s10, s10, 0x3500
	s_addc_u32 s11, s11, 0
	global_load_dword v0, v0, s[10:11] sc1


; __device__ __forceinline__ unsigned xb_ld(unsigned* p)              { return __hip_atomic_load(p, __ATOMIC_RELAXED, __HIP_MEMORY_SCOPE_AGENT); }
; #define XB_SPIN(cond, bar) do { unsigned _sp = 0; while (cond) { __builtin_amdgcn_s_sleep(1); \
;     if ((++_sp & 255u) == 0u) { if (xb_ld(&(bar)[XB_TMO])) break; if (_sp > XB_SPIN_CAP) { atomicAdd(&(bar)[XB_TMO], 1u); break; } } } } while (0)
; __device__ __forceinline__ void xcd_barrier(const XcdBarrier& b) {
;     ...
;             XB_SPIN(xb_ld(&bar[XB_XGEN(b.x)]) == gen, bar);
	s_waitcnt vmcnt(0)
	v_cmp_eq_u32_e32 vcc, v0, v1
	s_and_saveexec_b64 s[6:7], vcc
	s_cbranch_execz .LBB0_955
	v_readlane_b32 s12, v228, 2
	v_readlane_b32 s18, v228, 8
	v_readlane_b32 s13, v228, 3
	v_readlane_b32 s19, v228, 9
	s_add_u32 s8, s18, 0x179ed200
	v_readlane_b32 s14, v228, 4
	v_readlane_b32 s15, v228, 5
	s_addc_u32 s9, s19, 0
	s_mov_b32 s22, 1
	s_mov_b64 s[12:13], 0
	v_mov_b32_e32 v0, 0
	v_readlane_b32 s16, v228, 6
	v_readlane_b32 s17, v228, 7
	s_branch .LBB0_946

; __device__ __forceinline__ unsigned xb_ld(unsigned* p)              { return __hip_atomic_load(p, __ATOMIC_RELAXED, __HIP_MEMORY_SCOPE_AGENT); }
; __device__ __forceinline__ unsigned xb_add(unsigned* p, unsigned v) { return __hip_atomic_fetch_add(p, v, __ATOMIC_RELAXED, __HIP_MEMORY_SCOPE_AGENT); }
; #define XB_SPIN(cond, bar) do { unsigned _sp = 0; while (cond) { __builtin_amdgcn_s_sleep(1); \
;     if ((++_sp & 255u) == 0u) { if (xb_ld(&(bar)[XB_TMO])) break; if (_sp > XB_SPIN_CAP) { atomicAdd(&(bar)[XB_TMO], 1u); break; } } } } while (0)
; __device__ __forceinline__ void xcd_barrier(const XcdBarrier& b) {
;     ...
;         unsigned nloc = b.st[0], nx = b.st[1];
;         if (nloc == 0u) { xcd_barrier_complete(bar, b.x, nloc, nx); b.st[0] = nloc; b.st[1] = nx; }
;         const unsigned old = xb_add(&bar[XB_XSUB(b.x)], 1u);
;         const unsigned gen = old / nloc;
;         if (old + 1u == (gen + 1u) * nloc) {
;             __builtin_amdgcn_fence(__ATOMIC_RELEASE, "agent");
;             asm volatile("s_waitcnt vmcnt(0)" ::: "memory");
;             const unsigned og = xb_add(&bar[XB_TOP], 1u);
;             const unsigned tg = og / nx;
;             if (og + 1u == (tg + 1u) * nx) xb_add(&bar[XB_TOPGEN], 1u);
;             else XB_SPIN(xb_ld(&bar[XB_TOPGEN]) == tg, bar);
;             __builtin_amdgcn_fence(__ATOMIC_ACQUIRE, "agent");
;             xb_add(&bar[XB_XGEN(b.x)], 1u);
;             asm volatile("s_waitcnt vmcnt(0)" ::: "memory");
;         } else {
;             XB_SPIN(xb_ld(&bar[XB_XGEN(b.x)]) == gen, bar);
.LBB0_1194:
	s_or_b64 exec, exec, s[6:7]
	v_cvt_f32_u32_e32 v4, v2
	s_waitcnt vmcnt(0)
	v_readfirstlane_b32 s4, v3
	v_sub_u32_e32 v3, 0, v2
	v_rcp_iflag_f32_e32 v4, v4
	v_add_u32_e32 v5, s4, v0
	v_mul_f32_e32 v4, 0x4f7ffffe, v4
	v_cvt_u32_f32_e32 v4, v4
	v_mul_lo_u32 v0, v3, v4
	v_mul_hi_u32 v0, v4, v0
	v_add_u32_e32 v0, v4, v0
	v_mul_hi_u32 v0, v5, v0
	v_mul_lo_u32 v3, v0, v2
	v_sub_u32_e32 v3, v5, v3
	v_add_u32_e32 v4, 1, v0
	v_cmp_ge_u32_e32 vcc, v3, v2
	s_nop 1
	v_cndmask_b32_e32 v0, v0, v4, vcc
	v_sub_u32_e32 v4, v3, v2
	v_cndmask_b32_e32 v3, v3, v4, vcc
	v_add_u32_e32 v4, 1, v0
	v_cmp_ge_u32_e32 vcc, v3, v2
	v_add_u32_e32 v3, 1, v5
	s_nop 0
	v_cndmask_b32_e32 v0, v0, v4, vcc
	v_mul_lo_u32 v4, v2, v0
	v_add_u32_e32 v2, v4, v2
	v_cmp_ne_u32_e32 vcc, v3, v2
	s_and_saveexec_b64 s[4:5], vcc
	s_xor_b64 s[4:5], exec, s[4:5]
	s_cbranch_execz .LBB0_1208
	s_waitcnt lgkmcnt(0)
	v_readlane_b32 s10, v228, 15
	v_readlane_b32 s11, v228, 16
	v_mov_b32_e32 v1, 0
	s_nop 4
	s_add_u32 s10, s10, 0x3500
	s_addc_u32 s11, s11, 0
	global_load_dword v1, v1, s[10:11] sc1


; __device__ __forceinline__ unsigned xb_ld(unsigned* p)              { return __hip_atomic_load(p, __ATOMIC_RELAXED, __HIP_MEMORY_SCOPE_AGENT); }
; #define XB_SPIN(cond, bar) do { unsigned _sp = 0; while (cond) { __builtin_amdgcn_s_sleep(1); \
;     if ((++_sp & 255u) == 0u) { if (xb_ld(&(bar)[XB_TMO])) break; if (_sp > XB_SPIN_CAP) { atomicAdd(&(bar)[XB_TMO], 1u); break; } } } } while (0)
; __device__ __forceinline__ void xcd_barrier(const XcdBarrier& b) {
;     ...
;             XB_SPIN(xb_ld(&bar[XB_XGEN(b.x)]) == gen, bar);
	s_waitcnt vmcnt(0)
	v_cmp_eq_u32_e32 vcc, v1, v0
	s_and_saveexec_b64 s[6:7], vcc
	s_cbranch_execz .LBB0_1207
	v_readlane_b32 s12, v228, 2
	v_readlane_b32 s14, v228, 4
	v_readlane_b32 s15, v228, 5
	v_readlane_b32 s18, v228, 8
	v_readlane_b32 s19, v228, 9
	s_mov_b64 s[14:15], s[18:19]
	v_readlane_b32 s13, v228, 3
	s_add_u32 s8, s14, 0x179ed200
	s_addc_u32 s9, s15, 0
	s_mov_b32 s22, 1
	s_mov_b64 s[12:13], 0
	v_mov_b32_e32 v1, 0
	v_readlane_b32 s16, v228, 6
	v_readlane_b32 s17, v228, 7
	s_branch .LBB0_1198
